# P7 epilogue: residual rows fetched eight 16-byte loads at a time instead of load/wait/store per piece
# speedup vs baseline: 1.0238x; 1.0086x over previous
.LBB0_1036:
	s_add_u32 s0, s18, 0xfffc0080
	s_addc_u32 s1, s19, -1
	s_add_i32 s33, 0, 0x10000
	v_add_u32_e32 v140, s33, v164
	ds_read_b128 v[124:127], v140
	ds_read_b128 v[128:131], v140 offset:1024
	ds_read_b128 v[136:139], v140 offset:2048
	ds_read_b128 v[140:143], v140 offset:3072
	s_cmp_eq_u32 s59, 12
	s_cselect_b32 s23, s13, s1
	s_cselect_b32 s22, s55, s0
	s_cselect_b32 s21, s11, s58
	s_cselect_b32 s20, s56, s57
	v_lshl_add_u64 v[162:163], s[18:19], 0, v[154:155]
	s_add_i32 m0, s30, 0xc000
	ds_read_b128 v[158:161], v166
	ds_read_b128 v[168:171], v166 offset:1024
	ds_read_b128 v[172:175], v166 offset:2048
	ds_read_b128 v[176:179], v166 offset:3072
	ds_read_b128 v[180:183], v166 offset:4096
	ds_read_b128 v[184:187], v166 offset:5120
	ds_read_b128 v[188:191], v166 offset:6144
	ds_read_b128 v[192:195], v166 offset:7168
	global_load_lds_dwordx4 v[162:163], off
	v_lshl_add_u64 v[162:163], s[18:19], 0, v[156:157]
	s_add_i32 m0, s30, 0xe000
	s_nop 0
	global_load_lds_dwordx4 v[162:163], off
	s_waitcnt lgkmcnt(8)
	s_barrier
	s_waitcnt lgkmcnt(0)
	s_setprio 1
	s_waitcnt lgkmcnt(0)
	v_mfma_f32_16x16x32_bf16 v[132:135], v[124:127], v[158:161], v[132:135]
	v_mfma_f32_16x16x32_bf16 v[120:123], v[136:139], v[158:161], v[120:123]
	v_mfma_f32_16x16x32_bf16 v[108:111], v[124:127], v[172:175], v[108:111]
	v_mfma_f32_16x16x32_bf16 v[104:107], v[136:139], v[172:175], v[104:107]
	v_mfma_f32_16x16x32_bf16 v[92:95], v[124:127], v[180:183], v[92:95]
	v_mfma_f32_16x16x32_bf16 v[88:91], v[136:139], v[180:183], v[88:91]
	v_mfma_f32_16x16x32_bf16 v[76:79], v[124:127], v[188:191], v[76:79]
	v_mfma_f32_16x16x32_bf16 v[72:75], v[136:139], v[188:191], v[72:75]
	v_mfma_f32_16x16x32_bf16 v[132:135], v[128:131], v[168:171], v[132:135]
	v_mfma_f32_16x16x32_bf16 v[120:123], v[140:143], v[168:171], v[120:123]
	v_mfma_f32_16x16x32_bf16 v[108:111], v[128:131], v[176:179], v[108:111]
	v_mfma_f32_16x16x32_bf16 v[104:107], v[140:143], v[176:179], v[104:107]
	v_mfma_f32_16x16x32_bf16 v[92:95], v[128:131], v[184:187], v[92:95]
	v_mfma_f32_16x16x32_bf16 v[88:91], v[140:143], v[184:187], v[88:91]
	v_mfma_f32_16x16x32_bf16 v[76:79], v[128:131], v[192:195], v[76:79]
	v_mfma_f32_16x16x32_bf16 v[72:75], v[140:143], v[192:195], v[72:75]
	s_setprio 0
	s_barrier
	s_add_i32 s38, 0, 0x14000
	v_add_u32_e32 v162, s38, v164
	s_add_i32 s0, s33, s29
	ds_read_b128 v[196:199], v162
	ds_read_b128 v[200:203], v162 offset:1024
	ds_read_b128 v[204:207], v162 offset:2048
	ds_read_b128 v[208:211], v162 offset:3072
	v_lshl_add_u64 v[162:163], s[20:21], 0, v[144:145]
	s_mov_b32 m0, s0
	v_lshl_add_u64 v[212:213], s[20:21], 0, v[152:153]
	global_load_lds_dwordx4 v[162:163], off
	s_add_i32 m0, s0, 0x2000
	s_nop 0
	global_load_lds_dwordx4 v[212:213], off
	s_barrier
	s_waitcnt lgkmcnt(0)
	s_setprio 1
	s_waitcnt lgkmcnt(0)
	v_mfma_f32_16x16x32_bf16 v[116:119], v[196:199], v[158:161], v[116:119]
	v_mfma_f32_16x16x32_bf16 v[112:115], v[204:207], v[158:161], v[112:115]
	v_mfma_f32_16x16x32_bf16 v[100:103], v[196:199], v[172:175], v[100:103]
	v_mfma_f32_16x16x32_bf16 v[96:99], v[204:207], v[172:175], v[96:99]
	v_mfma_f32_16x16x32_bf16 v[84:87], v[196:199], v[180:183], v[84:87]
	v_mfma_f32_16x16x32_bf16 v[80:83], v[204:207], v[180:183], v[80:83]
	v_mfma_f32_16x16x32_bf16 v[68:71], v[196:199], v[188:191], v[68:71]
	v_mfma_f32_16x16x32_bf16 v[64:67], v[204:207], v[188:191], v[64:67]
	v_mfma_f32_16x16x32_bf16 v[116:119], v[200:203], v[168:171], v[116:119]
	v_mfma_f32_16x16x32_bf16 v[112:115], v[208:211], v[168:171], v[112:115]
	v_mfma_f32_16x16x32_bf16 v[100:103], v[200:203], v[176:179], v[100:103]
	v_mfma_f32_16x16x32_bf16 v[96:99], v[208:211], v[176:179], v[96:99]
	v_mfma_f32_16x16x32_bf16 v[84:87], v[200:203], v[184:187], v[84:87]
	v_mfma_f32_16x16x32_bf16 v[80:83], v[208:211], v[184:187], v[80:83]
	v_mfma_f32_16x16x32_bf16 v[68:71], v[200:203], v[192:195], v[68:71]
	v_mfma_f32_16x16x32_bf16 v[64:67], v[208:211], v[192:195], v[64:67]
	s_setprio 0
	s_mov_b32 m0, s30
	v_lshl_add_u64 v[214:215], s[22:23], 0, v[144:145]
	s_barrier
	ds_read_b128 v[158:161], v166 offset:16384
	ds_read_b128 v[168:171], v166 offset:17408
	ds_read_b128 v[172:175], v166 offset:18432
	ds_read_b128 v[176:179], v166 offset:19456
	ds_read_b128 v[180:183], v166 offset:20480
	ds_read_b128 v[184:187], v166 offset:21504
	ds_read_b128 v[188:191], v166 offset:22528
	ds_read_b128 v[192:195], v166 offset:23552
	global_load_lds_dwordx4 v[214:215], off
	v_lshl_add_u64 v[216:217], s[22:23], 0, v[152:153]
	s_mov_b32 m0, s31
	s_nop 0
	global_load_lds_dwordx4 v[216:217], off
	s_barrier
	s_waitcnt lgkmcnt(0)
	s_setprio 1
	s_waitcnt lgkmcnt(0)
	v_mfma_f32_16x16x32_bf16 v[60:63], v[124:127], v[158:161], v[60:63]
	v_mfma_f32_16x16x32_bf16 v[56:59], v[136:139], v[158:161], v[56:59]
	v_mfma_f32_16x16x32_bf16 v[44:47], v[124:127], v[172:175], v[44:47]
	v_mfma_f32_16x16x32_bf16 v[40:43], v[136:139], v[172:175], v[40:43]
	v_mfma_f32_16x16x32_bf16 v[28:31], v[124:127], v[180:183], v[28:31]
	v_mfma_f32_16x16x32_bf16 v[24:27], v[136:139], v[180:183], v[24:27]
	v_mfma_f32_16x16x32_bf16 v[12:15], v[124:127], v[188:191], v[12:15]
	v_mfma_f32_16x16x32_bf16 v[8:11], v[136:139], v[188:191], v[8:11]
	v_mfma_f32_16x16x32_bf16 v[60:63], v[128:131], v[168:171], v[60:63]
	v_mfma_f32_16x16x32_bf16 v[56:59], v[140:143], v[168:171], v[56:59]
	v_mfma_f32_16x16x32_bf16 v[44:47], v[128:131], v[176:179], v[44:47]
	v_mfma_f32_16x16x32_bf16 v[40:43], v[140:143], v[176:179], v[40:43]
	v_mfma_f32_16x16x32_bf16 v[28:31], v[128:131], v[184:187], v[28:31]
	v_mfma_f32_16x16x32_bf16 v[24:27], v[140:143], v[184:187], v[24:27]
	v_mfma_f32_16x16x32_bf16 v[12:15], v[128:131], v[192:195], v[12:15]
	v_mfma_f32_16x16x32_bf16 v[8:11], v[140:143], v[192:195], v[8:11]
	s_setprio 0
	s_barrier
	s_add_u32 s0, s20, 0x40000
	s_addc_u32 s1, s21, 0
	s_add_i32 s33, s38, s29
	v_lshl_add_u64 v[124:125], s[0:1], 0, v[144:145]
	s_mov_b32 m0, s33
	s_nop 0
	global_load_lds_dwordx4 v[124:125], off
	v_lshl_add_u64 v[124:125], s[0:1], 0, v[152:153]
	s_add_i32 m0, s33, 0x2000
	s_nop 0
	global_load_lds_dwordx4 v[124:125], off
	s_waitcnt vmcnt(6)
	s_barrier
	s_setprio 1
	v_mfma_f32_16x16x32_bf16 v[52:55], v[196:199], v[158:161], v[52:55]
	v_mfma_f32_16x16x32_bf16 v[48:51], v[204:207], v[158:161], v[48:51]
	v_mfma_f32_16x16x32_bf16 v[36:39], v[196:199], v[172:175], v[36:39]
	v_mfma_f32_16x16x32_bf16 v[32:35], v[204:207], v[172:175], v[32:35]
	v_mfma_f32_16x16x32_bf16 v[20:23], v[196:199], v[180:183], v[20:23]
	v_mfma_f32_16x16x32_bf16 v[16:19], v[204:207], v[180:183], v[16:19]
	v_mfma_f32_16x16x32_bf16 v[4:7], v[196:199], v[188:191], v[4:7]
	v_mfma_f32_16x16x32_bf16 v[0:3], v[204:207], v[188:191], v[0:3]
	v_mfma_f32_16x16x32_bf16 v[52:55], v[200:203], v[168:171], v[52:55]
	v_mfma_f32_16x16x32_bf16 v[48:51], v[208:211], v[168:171], v[48:51]
	v_mfma_f32_16x16x32_bf16 v[36:39], v[200:203], v[176:179], v[36:39]
	v_mfma_f32_16x16x32_bf16 v[32:35], v[208:211], v[176:179], v[32:35]
	v_mfma_f32_16x16x32_bf16 v[20:23], v[200:203], v[184:187], v[20:23]
	v_mfma_f32_16x16x32_bf16 v[16:19], v[208:211], v[184:187], v[16:19]
	v_mfma_f32_16x16x32_bf16 v[4:7], v[200:203], v[192:195], v[4:7]
	v_mfma_f32_16x16x32_bf16 v[0:3], v[208:211], v[192:195], v[0:3]
	s_setprio 0
	s_add_i32 s33, 0, 0x18000
	v_add_u32_e32 v140, s33, v164
	s_barrier
	ds_read_b128 v[124:127], v140
	ds_read_b128 v[128:131], v140 offset:1024
	ds_read_b128 v[136:139], v140 offset:2048
	ds_read_b128 v[140:143], v140 offset:3072
	s_add_u32 s0, s22, 0x40000
	s_addc_u32 s1, s23, 0
	s_mov_b32 m0, s34
	v_lshl_add_u64 v[196:197], s[0:1], 0, v[144:145]
	ds_read_b128 v[158:161], v166 offset:32768
	ds_read_b128 v[168:171], v166 offset:33792
	ds_read_b128 v[172:175], v166 offset:34816
	ds_read_b128 v[176:179], v166 offset:35840
	ds_read_b128 v[180:183], v166 offset:36864
	ds_read_b128 v[184:187], v166 offset:37888
	ds_read_b128 v[188:191], v166 offset:38912
	ds_read_b128 v[192:195], v166 offset:39936
	global_load_lds_dwordx4 v[196:197], off
	v_lshl_add_u64 v[196:197], s[0:1], 0, v[152:153]
	s_mov_b32 m0, s35
	s_nop 0
	global_load_lds_dwordx4 v[196:197], off
	s_waitcnt lgkmcnt(8)
	s_barrier
	s_waitcnt lgkmcnt(0)
	s_setprio 1
	s_waitcnt lgkmcnt(0)
	v_mfma_f32_16x16x32_bf16 v[132:135], v[124:127], v[158:161], v[132:135]
	v_mfma_f32_16x16x32_bf16 v[120:123], v[136:139], v[158:161], v[120:123]
	v_mfma_f32_16x16x32_bf16 v[108:111], v[124:127], v[172:175], v[108:111]
	v_mfma_f32_16x16x32_bf16 v[104:107], v[136:139], v[172:175], v[104:107]
	v_mfma_f32_16x16x32_bf16 v[92:95], v[124:127], v[180:183], v[92:95]
	v_mfma_f32_16x16x32_bf16 v[88:91], v[136:139], v[180:183], v[88:91]
	v_mfma_f32_16x16x32_bf16 v[76:79], v[124:127], v[188:191], v[76:79]
	v_mfma_f32_16x16x32_bf16 v[72:75], v[136:139], v[188:191], v[72:75]
	v_mfma_f32_16x16x32_bf16 v[132:135], v[128:131], v[168:171], v[132:135]
	v_mfma_f32_16x16x32_bf16 v[120:123], v[140:143], v[168:171], v[120:123]
	v_mfma_f32_16x16x32_bf16 v[108:111], v[128:131], v[176:179], v[108:111]
	v_mfma_f32_16x16x32_bf16 v[104:107], v[140:143], v[176:179], v[104:107]
	v_mfma_f32_16x16x32_bf16 v[92:95], v[128:131], v[184:187], v[92:95]
	v_mfma_f32_16x16x32_bf16 v[88:91], v[140:143], v[184:187], v[88:91]
	v_mfma_f32_16x16x32_bf16 v[76:79], v[128:131], v[192:195], v[76:79]
	v_mfma_f32_16x16x32_bf16 v[72:75], v[140:143], v[192:195], v[72:75]
	s_setprio 0
	s_barrier
	s_add_i32 s22, 0, 0x1c000
	s_add_i32 s0, s33, s29
	v_add_u32_e32 v167, s22, v164
	v_lshl_add_u64 v[162:163], v[162:163], 0, s[86:87]
	s_mov_b32 m0, s0
	ds_read_b128 v[196:199], v167
	ds_read_b128 v[200:203], v167 offset:1024
	ds_read_b128 v[204:207], v167 offset:2048
	ds_read_b128 v[208:211], v167 offset:3072
	global_load_lds_dwordx4 v[162:163], off
	v_lshl_add_u64 v[162:163], v[212:213], 0, s[86:87]
	s_add_i32 m0, s0, 0x2000
	s_nop 0
	global_load_lds_dwordx4 v[162:163], off
	s_barrier
	s_waitcnt lgkmcnt(0)
	s_setprio 1
	s_waitcnt lgkmcnt(0)
	v_mfma_f32_16x16x32_bf16 v[116:119], v[196:199], v[158:161], v[116:119]
	v_mfma_f32_16x16x32_bf16 v[112:115], v[204:207], v[158:161], v[112:115]
	v_mfma_f32_16x16x32_bf16 v[100:103], v[196:199], v[172:175], v[100:103]
	v_mfma_f32_16x16x32_bf16 v[96:99], v[204:207], v[172:175], v[96:99]
	v_mfma_f32_16x16x32_bf16 v[84:87], v[196:199], v[180:183], v[84:87]
	v_mfma_f32_16x16x32_bf16 v[80:83], v[204:207], v[180:183], v[80:83]
	v_mfma_f32_16x16x32_bf16 v[68:71], v[196:199], v[188:191], v[68:71]
	v_mfma_f32_16x16x32_bf16 v[64:67], v[204:207], v[188:191], v[64:67]
	v_mfma_f32_16x16x32_bf16 v[116:119], v[200:203], v[168:171], v[116:119]
	v_mfma_f32_16x16x32_bf16 v[112:115], v[208:211], v[168:171], v[112:115]
	v_mfma_f32_16x16x32_bf16 v[100:103], v[200:203], v[176:179], v[100:103]
	v_mfma_f32_16x16x32_bf16 v[96:99], v[208:211], v[176:179], v[96:99]
	v_mfma_f32_16x16x32_bf16 v[84:87], v[200:203], v[184:187], v[84:87]
	v_mfma_f32_16x16x32_bf16 v[80:83], v[208:211], v[184:187], v[80:83]
	v_mfma_f32_16x16x32_bf16 v[68:71], v[200:203], v[192:195], v[68:71]
	v_mfma_f32_16x16x32_bf16 v[64:67], v[208:211], v[192:195], v[64:67]
	s_setprio 0
	s_mov_b32 m0, s44
	v_lshl_add_u64 v[162:163], v[214:215], 0, s[86:87]
	s_barrier
	ds_read_b128 v[158:161], v166 offset:49152
	ds_read_b128 v[168:171], v166 offset:50176
	ds_read_b128 v[172:175], v166 offset:51200
	ds_read_b128 v[176:179], v166 offset:52224
	ds_read_b128 v[180:183], v166 offset:53248
	ds_read_b128 v[184:187], v166 offset:54272
	ds_read_b128 v[188:191], v166 offset:55296
	ds_read_b128 v[192:195], v166 offset:56320
	global_load_lds_dwordx4 v[162:163], off
	v_lshl_add_u64 v[162:163], v[216:217], 0, s[86:87]
	s_mov_b32 m0, s45
	s_nop 0
	global_load_lds_dwordx4 v[162:163], off
	s_barrier
	s_waitcnt lgkmcnt(0)
	s_setprio 1
	s_waitcnt lgkmcnt(0)
	v_mfma_f32_16x16x32_bf16 v[60:63], v[124:127], v[158:161], v[60:63]
	v_mfma_f32_16x16x32_bf16 v[56:59], v[136:139], v[158:161], v[56:59]
	v_mfma_f32_16x16x32_bf16 v[44:47], v[124:127], v[172:175], v[44:47]
	v_mfma_f32_16x16x32_bf16 v[40:43], v[136:139], v[172:175], v[40:43]
	v_mfma_f32_16x16x32_bf16 v[28:31], v[124:127], v[180:183], v[28:31]
	v_mfma_f32_16x16x32_bf16 v[24:27], v[136:139], v[180:183], v[24:27]
	v_mfma_f32_16x16x32_bf16 v[12:15], v[124:127], v[188:191], v[12:15]
	v_mfma_f32_16x16x32_bf16 v[8:11], v[136:139], v[188:191], v[8:11]
	v_mfma_f32_16x16x32_bf16 v[60:63], v[128:131], v[168:171], v[60:63]
	v_mfma_f32_16x16x32_bf16 v[56:59], v[140:143], v[168:171], v[56:59]
	v_mfma_f32_16x16x32_bf16 v[44:47], v[128:131], v[176:179], v[44:47]
	v_mfma_f32_16x16x32_bf16 v[40:43], v[140:143], v[176:179], v[40:43]
	v_mfma_f32_16x16x32_bf16 v[28:31], v[128:131], v[184:187], v[28:31]
	v_mfma_f32_16x16x32_bf16 v[24:27], v[140:143], v[184:187], v[24:27]
	v_mfma_f32_16x16x32_bf16 v[12:15], v[128:131], v[192:195], v[12:15]
	v_mfma_f32_16x16x32_bf16 v[8:11], v[140:143], v[192:195], v[8:11]
	s_setprio 0
	s_barrier
	s_add_u32 s0, s20, 0x40080
	s_addc_u32 s1, s21, 0
	s_add_i32 s20, s22, s29
	v_lshl_add_u64 v[124:125], s[0:1], 0, v[144:145]
	s_mov_b32 m0, s20
	s_nop 0
	global_load_lds_dwordx4 v[124:125], off
	v_lshl_add_u64 v[124:125], s[0:1], 0, v[152:153]
	s_add_i32 m0, s20, 0x2000
	s_nop 0
	global_load_lds_dwordx4 v[124:125], off
	s_waitcnt vmcnt(6)
	s_barrier
	s_setprio 1
	v_mfma_f32_16x16x32_bf16 v[52:55], v[196:199], v[158:161], v[52:55]
	v_mfma_f32_16x16x32_bf16 v[48:51], v[204:207], v[158:161], v[48:51]
	v_mfma_f32_16x16x32_bf16 v[36:39], v[196:199], v[172:175], v[36:39]
	v_mfma_f32_16x16x32_bf16 v[32:35], v[204:207], v[172:175], v[32:35]
	v_mfma_f32_16x16x32_bf16 v[20:23], v[196:199], v[180:183], v[20:23]
	v_mfma_f32_16x16x32_bf16 v[16:19], v[204:207], v[180:183], v[16:19]
	v_mfma_f32_16x16x32_bf16 v[4:7], v[196:199], v[188:191], v[4:7]
	v_mfma_f32_16x16x32_bf16 v[0:3], v[204:207], v[188:191], v[0:3]
	v_mfma_f32_16x16x32_bf16 v[52:55], v[200:203], v[168:171], v[52:55]
	v_mfma_f32_16x16x32_bf16 v[48:51], v[208:211], v[168:171], v[48:51]
	v_mfma_f32_16x16x32_bf16 v[36:39], v[200:203], v[176:179], v[36:39]
	v_mfma_f32_16x16x32_bf16 v[32:35], v[208:211], v[176:179], v[32:35]
	v_mfma_f32_16x16x32_bf16 v[20:23], v[200:203], v[184:187], v[20:23]
	v_mfma_f32_16x16x32_bf16 v[16:19], v[208:211], v[184:187], v[16:19]
	v_mfma_f32_16x16x32_bf16 v[4:7], v[200:203], v[192:195], v[4:7]
	v_mfma_f32_16x16x32_bf16 v[0:3], v[208:211], v[192:195], v[0:3]
	s_setprio 0
	s_add_i32 s59, s59, 2
	s_add_u32 s18, s18, 0x100
	s_addc_u32 s19, s19, 0
	s_add_u32 s57, s57, 0x100
	s_addc_u32 s58, s58, 0
	s_cmp_gt_u32 s59, 13
	s_barrier
	s_cbranch_scc0 .LBB0_1036
	s_ashr_i32 s0, s49, 4
	s_mul_i32 s0, s0, 3
	v_lshl_add_u32 v162, s49, 8, v146
	v_lshl_or_b32 v160, s54, 8, v165
	s_ashr_i32 s1, s0, 31
	v_ashrrev_i32_e32 v163, 31, v162
	s_lshl_b64 s[0:1], s[0:1], 12
	v_ashrrev_i32_e32 v161, 31, v160
	v_lshlrev_b64 v[158:159], 10, v[162:163]
	s_add_u32 s0, s36, s0
	v_lshl_add_u64 v[158:159], v[158:159], 0, v[160:161]
	s_addc_u32 s1, s37, s1
	v_lshlrev_b64 v[158:159], 2, v[158:159]
	v_lshl_add_u64 v[124:125], v[160:161], 2, s[0:1]
	v_lshl_add_u64 v[172:173], s[6:7], 0, v[158:159]
	global_load_dwordx4 v[140:143], v[124:125], off
	global_load_dwordx4 v[136:139], v[124:125], off offset:64
	global_load_dwordx4 v[128:131], v[124:125], off offset:512
	s_nop 0
	global_load_dwordx4 v[124:127], v[124:125], off offset:576
	s_mov_b64 s[0:1], 0x80000
	s_and_b64 vcc, exec, s[4:5]
	s_mov_b32 s54, s10
	s_mov_b32 s49, s12
	s_mov_b64 s[20:21], s[16:17]
	s_mov_b64 s[18:19], s[14:15]
	v_lshl_add_u64 v[210:211], s[6:7], 0, v[158:159]
	global_load_dwordx4 v[174:177], v[210:211], off
	global_load_dwordx4 v[178:181], v[210:211], off offset:64
	global_load_dwordx4 v[182:185], v[210:211], off offset:512
	global_load_dwordx4 v[186:189], v[210:211], off offset:576
	s_mov_b64 s[0:1], 0x10000
	v_lshl_add_u64 v[210:211], v[158:159], 0, s[0:1]
	v_lshl_add_u64 v[210:211], s[6:7], 0, v[210:211]
	global_load_dwordx4 v[190:193], v[210:211], off
	global_load_dwordx4 v[194:197], v[210:211], off offset:64
	global_load_dwordx4 v[198:201], v[210:211], off offset:512
	global_load_dwordx4 v[202:205], v[210:211], off offset:576
	v_lshl_add_u64 v[168:169], s[8:9], 0, v[158:159]
	s_waitcnt vmcnt(7)
	v_pk_fma_f32 v[134:135], v[134:135], v[142:143], v[176:177]
	v_pk_fma_f32 v[132:133], v[132:133], v[140:141], v[174:175]
	global_store_dwordx4 v[168:169], v[132:135], off
	s_waitcnt vmcnt(7)
	v_pk_fma_f32 v[122:123], v[122:123], v[138:139], v[180:181]
	v_pk_fma_f32 v[120:121], v[120:121], v[136:137], v[178:179]
	global_store_dwordx4 v[168:169], v[120:123], off offset:64
	s_waitcnt vmcnt(7)
	v_pk_fma_f32 v[118:119], v[118:119], v[130:131], v[184:185]
	v_pk_fma_f32 v[116:117], v[116:117], v[128:129], v[182:183]
	global_store_dwordx4 v[168:169], v[116:119], off offset:512
	s_waitcnt vmcnt(7)
	v_pk_fma_f32 v[114:115], v[114:115], v[126:127], v[188:189]
	v_pk_fma_f32 v[112:113], v[112:113], v[124:125], v[186:187]
	global_store_dwordx4 v[168:169], v[112:115], off offset:576
	s_mov_b64 s[0:1], 0x10000
	v_lshl_add_u64 v[168:169], v[158:159], 0, s[0:1]
	v_lshl_add_u64 v[168:169], s[8:9], 0, v[168:169]
	s_waitcnt vmcnt(7)
	v_pk_fma_f32 v[110:111], v[110:111], v[142:143], v[192:193]
	v_pk_fma_f32 v[108:109], v[108:109], v[140:141], v[190:191]
	global_store_dwordx4 v[168:169], v[108:111], off
	s_waitcnt vmcnt(7)
	v_pk_fma_f32 v[106:107], v[106:107], v[138:139], v[196:197]
	v_pk_fma_f32 v[104:105], v[104:105], v[136:137], v[194:195]
	global_store_dwordx4 v[168:169], v[104:107], off offset:64
	s_waitcnt vmcnt(7)
	v_pk_fma_f32 v[102:103], v[102:103], v[130:131], v[200:201]
	v_pk_fma_f32 v[100:101], v[100:101], v[128:129], v[198:199]
	global_store_dwordx4 v[168:169], v[100:103], off offset:512
	s_waitcnt vmcnt(7)
	v_pk_fma_f32 v[98:99], v[98:99], v[126:127], v[204:205]
	v_pk_fma_f32 v[96:97], v[96:97], v[124:125], v[202:203]
	global_store_dwordx4 v[168:169], v[96:99], off offset:576
	s_mov_b64 s[0:1], 0x20000
	v_lshl_add_u64 v[210:211], v[158:159], 0, s[0:1]
	v_lshl_add_u64 v[210:211], s[6:7], 0, v[210:211]
	global_load_dwordx4 v[174:177], v[210:211], off
	global_load_dwordx4 v[178:181], v[210:211], off offset:64
	global_load_dwordx4 v[182:185], v[210:211], off offset:512
	global_load_dwordx4 v[186:189], v[210:211], off offset:576
	s_mov_b64 s[0:1], 0x30000
	v_lshl_add_u64 v[210:211], v[158:159], 0, s[0:1]
	v_lshl_add_u64 v[210:211], s[6:7], 0, v[210:211]
	global_load_dwordx4 v[190:193], v[210:211], off
	global_load_dwordx4 v[194:197], v[210:211], off offset:64
	global_load_dwordx4 v[198:201], v[210:211], off offset:512
	global_load_dwordx4 v[202:205], v[210:211], off offset:576
	s_mov_b64 s[0:1], 0x20000
	v_lshl_add_u64 v[168:169], v[158:159], 0, s[0:1]
	v_lshl_add_u64 v[168:169], s[8:9], 0, v[168:169]
	s_waitcnt vmcnt(7)
	v_pk_fma_f32 v[94:95], v[94:95], v[142:143], v[176:177]
	v_pk_fma_f32 v[92:93], v[92:93], v[140:141], v[174:175]
	global_store_dwordx4 v[168:169], v[92:95], off
	s_waitcnt vmcnt(7)
	v_pk_fma_f32 v[90:91], v[90:91], v[138:139], v[180:181]
	v_pk_fma_f32 v[88:89], v[88:89], v[136:137], v[178:179]
	global_store_dwordx4 v[168:169], v[88:91], off offset:64
	s_waitcnt vmcnt(7)
	v_pk_fma_f32 v[86:87], v[86:87], v[130:131], v[184:185]
	v_pk_fma_f32 v[84:85], v[84:85], v[128:129], v[182:183]
	global_store_dwordx4 v[168:169], v[84:87], off offset:512
	s_waitcnt vmcnt(7)
	v_pk_fma_f32 v[82:83], v[82:83], v[126:127], v[188:189]
	v_pk_fma_f32 v[80:81], v[80:81], v[124:125], v[186:187]
	global_store_dwordx4 v[168:169], v[80:83], off offset:576
	s_mov_b64 s[0:1], 0x30000
	v_lshl_add_u64 v[168:169], v[158:159], 0, s[0:1]
	v_lshl_add_u64 v[168:169], s[8:9], 0, v[168:169]
	s_waitcnt vmcnt(7)
	v_pk_fma_f32 v[78:79], v[78:79], v[142:143], v[192:193]
	v_pk_fma_f32 v[76:77], v[76:77], v[140:141], v[190:191]
	global_store_dwordx4 v[168:169], v[76:79], off
	s_waitcnt vmcnt(7)
	v_pk_fma_f32 v[74:75], v[74:75], v[138:139], v[196:197]
	v_pk_fma_f32 v[72:73], v[72:73], v[136:137], v[194:195]
	global_store_dwordx4 v[168:169], v[72:75], off offset:64
	s_waitcnt vmcnt(7)
	v_pk_fma_f32 v[70:71], v[70:71], v[130:131], v[200:201]
	v_pk_fma_f32 v[68:69], v[68:69], v[128:129], v[198:199]
	global_store_dwordx4 v[168:169], v[68:71], off offset:512
	s_waitcnt vmcnt(7)
	v_pk_fma_f32 v[66:67], v[66:67], v[126:127], v[204:205]
	v_pk_fma_f32 v[64:65], v[64:65], v[124:125], v[202:203]
	global_store_dwordx4 v[168:169], v[64:67], off offset:576
	s_mov_b64 s[0:1], 0x80000
	v_lshl_add_u64 v[210:211], v[158:159], 0, s[0:1]
	v_lshl_add_u64 v[210:211], s[6:7], 0, v[210:211]
	global_load_dwordx4 v[174:177], v[210:211], off
	global_load_dwordx4 v[178:181], v[210:211], off offset:64
	global_load_dwordx4 v[182:185], v[210:211], off offset:512
	global_load_dwordx4 v[186:189], v[210:211], off offset:576
	s_mov_b64 s[0:1], 0x90000
	v_lshl_add_u64 v[210:211], v[158:159], 0, s[0:1]
	v_lshl_add_u64 v[210:211], s[6:7], 0, v[210:211]
	global_load_dwordx4 v[190:193], v[210:211], off
	global_load_dwordx4 v[194:197], v[210:211], off offset:64
	global_load_dwordx4 v[198:201], v[210:211], off offset:512
	global_load_dwordx4 v[202:205], v[210:211], off offset:576
	s_mov_b64 s[0:1], 0x80000
	v_lshl_add_u64 v[168:169], v[158:159], 0, s[0:1]
	v_lshl_add_u64 v[168:169], s[8:9], 0, v[168:169]
	s_waitcnt vmcnt(7)
	v_pk_fma_f32 v[62:63], v[62:63], v[142:143], v[176:177]
	v_pk_fma_f32 v[60:61], v[60:61], v[140:141], v[174:175]
	global_store_dwordx4 v[168:169], v[60:63], off
	s_waitcnt vmcnt(7)
	v_pk_fma_f32 v[58:59], v[58:59], v[138:139], v[180:181]
	v_pk_fma_f32 v[56:57], v[56:57], v[136:137], v[178:179]
	global_store_dwordx4 v[168:169], v[56:59], off offset:64
	s_waitcnt vmcnt(7)
	v_pk_fma_f32 v[54:55], v[54:55], v[130:131], v[184:185]
	v_pk_fma_f32 v[52:53], v[52:53], v[128:129], v[182:183]
	global_store_dwordx4 v[168:169], v[52:55], off offset:512
	s_waitcnt vmcnt(7)
	v_pk_fma_f32 v[50:51], v[50:51], v[126:127], v[188:189]
	v_pk_fma_f32 v[48:49], v[48:49], v[124:125], v[186:187]
	global_store_dwordx4 v[168:169], v[48:51], off offset:576
	s_mov_b64 s[0:1], 0x90000
	v_lshl_add_u64 v[168:169], v[158:159], 0, s[0:1]
	v_lshl_add_u64 v[168:169], s[8:9], 0, v[168:169]
	s_waitcnt vmcnt(7)
	v_pk_fma_f32 v[46:47], v[46:47], v[142:143], v[192:193]
	v_pk_fma_f32 v[44:45], v[44:45], v[140:141], v[190:191]
	global_store_dwordx4 v[168:169], v[44:47], off
	s_waitcnt vmcnt(7)
	v_pk_fma_f32 v[42:43], v[42:43], v[138:139], v[196:197]
	v_pk_fma_f32 v[40:41], v[40:41], v[136:137], v[194:195]
	global_store_dwordx4 v[168:169], v[40:43], off offset:64
	s_waitcnt vmcnt(7)
	v_pk_fma_f32 v[38:39], v[38:39], v[130:131], v[200:201]
	v_pk_fma_f32 v[36:37], v[36:37], v[128:129], v[198:199]
	global_store_dwordx4 v[168:169], v[36:39], off offset:512
	s_waitcnt vmcnt(7)
	v_pk_fma_f32 v[34:35], v[34:35], v[126:127], v[204:205]
	v_pk_fma_f32 v[32:33], v[32:33], v[124:125], v[202:203]
	global_store_dwordx4 v[168:169], v[32:35], off offset:576
	s_mov_b64 s[0:1], 0xa0000
	v_lshl_add_u64 v[210:211], v[158:159], 0, s[0:1]
	v_lshl_add_u64 v[210:211], s[6:7], 0, v[210:211]
	global_load_dwordx4 v[174:177], v[210:211], off
	global_load_dwordx4 v[178:181], v[210:211], off offset:64
	global_load_dwordx4 v[182:185], v[210:211], off offset:512
	global_load_dwordx4 v[186:189], v[210:211], off offset:576
	s_mov_b64 s[0:1], 0xb0000
	v_lshl_add_u64 v[210:211], v[158:159], 0, s[0:1]
	v_lshl_add_u64 v[210:211], s[6:7], 0, v[210:211]
	global_load_dwordx4 v[190:193], v[210:211], off
	global_load_dwordx4 v[194:197], v[210:211], off offset:64
	global_load_dwordx4 v[198:201], v[210:211], off offset:512
	global_load_dwordx4 v[202:205], v[210:211], off offset:576
	s_mov_b64 s[0:1], 0xa0000
	v_lshl_add_u64 v[168:169], v[158:159], 0, s[0:1]
	v_lshl_add_u64 v[168:169], s[8:9], 0, v[168:169]
	s_waitcnt vmcnt(7)
	v_pk_fma_f32 v[30:31], v[30:31], v[142:143], v[176:177]
	v_pk_fma_f32 v[28:29], v[28:29], v[140:141], v[174:175]
	global_store_dwordx4 v[168:169], v[28:31], off
	s_waitcnt vmcnt(7)
	v_pk_fma_f32 v[26:27], v[26:27], v[138:139], v[180:181]
	v_pk_fma_f32 v[24:25], v[24:25], v[136:137], v[178:179]
	global_store_dwordx4 v[168:169], v[24:27], off offset:64
	s_waitcnt vmcnt(7)
	v_pk_fma_f32 v[22:23], v[22:23], v[130:131], v[184:185]
	v_pk_fma_f32 v[20:21], v[20:21], v[128:129], v[182:183]
	global_store_dwordx4 v[168:169], v[20:23], off offset:512
	s_waitcnt vmcnt(7)
	v_pk_fma_f32 v[18:19], v[18:19], v[126:127], v[188:189]
	v_pk_fma_f32 v[16:17], v[16:17], v[124:125], v[186:187]
	global_store_dwordx4 v[168:169], v[16:19], off offset:576
	s_mov_b64 s[0:1], 0xb0000
	v_lshl_add_u64 v[168:169], v[158:159], 0, s[0:1]
	v_lshl_add_u64 v[168:169], s[8:9], 0, v[168:169]
	s_waitcnt vmcnt(7)
	v_pk_fma_f32 v[14:15], v[14:15], v[142:143], v[192:193]
	v_pk_fma_f32 v[12:13], v[12:13], v[140:141], v[190:191]
	global_store_dwordx4 v[168:169], v[12:15], off
	s_waitcnt vmcnt(7)
	v_pk_fma_f32 v[10:11], v[10:11], v[138:139], v[196:197]
	v_pk_fma_f32 v[8:9], v[8:9], v[136:137], v[194:195]
	global_store_dwordx4 v[168:169], v[8:11], off offset:64
	s_waitcnt vmcnt(7)
	v_pk_fma_f32 v[6:7], v[6:7], v[130:131], v[200:201]
	v_pk_fma_f32 v[4:5], v[4:5], v[128:129], v[198:199]
	global_store_dwordx4 v[168:169], v[4:7], off offset:512
	s_waitcnt vmcnt(7)
	v_pk_fma_f32 v[2:3], v[2:3], v[126:127], v[204:205]
	v_pk_fma_f32 v[0:1], v[0:1], v[124:125], v[202:203]
	global_store_dwordx4 v[168:169], v[0:3], off offset:576
	s_cbranch_vccz .LBB0_1029
	s_waitcnt vmcnt(0)
	s_cmpk_gt_u32 s24, 0xff
	s_cbranch_scc1 .LBB0_1040
	s_barrier
